# overlap GLA scan with dilated attention: waves0-3 scan first, waves4-7 attention first (branch-only edit)
# speedup vs baseline: 1.0104x; 1.0104x over previous
; __device__ __forceinline__ void gla_summ_unit(const P& p, int unit, const SummRaw& raw) {
;     ...
; #pragma unroll 1
;   for (int tI = 0; tI < 8; ++tI) {
;     int tile = wid * 8 + tI;
;     int dir = tile >> 5, dkt = (tile >> 3) & 3, dvt = tile & 7;
;     const u16* Asrc = (dir ? kdbT : kdfT) + (dkt * 16 + fr) * LP + fq * 8;
;     const u16* Bsrc = vT + (dvt * 16 + fr) * LP + fq * 8;
;     f32x4 d = {0.f, 0.f, 0.f, 0.f};
; #pragma unroll
;     for (int ks = 0; ks < 2; ++ks) {
;       bf16x8 a = *(const bf16x8*)(Asrc + ks * 32);
;       bf16x8 b = *(const bf16x8*)(Bsrc + ks * 32);
;       d = __builtin_amdgcn_mfma_f32_16x16x32_bf16(a, b, d, 0, 0, 0);
;     }
;     uint2 w; w.x = pack2(d[0], d[1]); w.y = pack2(d[2], d[3]);
;     *(uint2*)(kvout + (size_t)(unit * 2 + dir) * 8192 + (dvt * 16 + fr) * 64 + dkt * 16 + fq * 4) = w;
;   }
; __device__ void phase_gla_summ(const P& p) {
;     ...
;   for (; u < 4096; u += gridDim.x) {
;     int un = u + gridDim.x;
;     SummRaw nxt = gla_summ_load(p, un < 4096 ? un : u, tid);
;     gla_summ_unit(p, u, cur);
;     cur = nxt;
;   }
.LBB0_227:
	v_add_u32_e32 v31, s0, v30
	v_add_u32_e32 v34, 0x11200, v31
	s_nop 0
	ds_read_b128 v[42:45], v34
	v_add_u32_e32 v31, 0x11240, v31
	ds_read_b128 v[52:55], v31
	s_addk_i32 s0, 0x900
	s_cmpk_lg_i32 s0, 0x4800
	s_waitcnt lgkmcnt(1)
	v_mfma_f32_16x16x32_bf16 v[42:45], v[8:11], v[42:45], 0
	s_waitcnt lgkmcnt(0)
	v_mfma_f32_16x16x32_bf16 v[42:45], v[12:15], v[52:55], v[42:45]
	s_nop 7
	v_cvt_pk_bf16_f32 v42, v42, v43
	v_cvt_pk_bf16_f32 v43, v44, v45
	global_store_dwordx2 v[28:29], v[42:43], off offset:-4
	v_lshl_add_u64 v[28:29], v[28:29], 0, s[22:23]
	s_cbranch_scc1 .LBB0_227
	s_waitcnt lgkmcnt(0)
	s_add_i32 s20, s20, s3
	s_andn2_b64 vcc, exec, s[24:25]
	s_mov_b32 s21, s46
	s_waitcnt vmcnt(3)
	v_mov_b64_e32 v[12:13], v[20:21]
	v_mov_b64_e32 v[14:15], v[22:23]
	s_waitcnt vmcnt(1)
	v_mov_b64_e32 v[8:9], v[24:25]
	v_mov_b64_e32 v[10:11], v[26:27]
	v_mov_b64_e32 v[28:29], v[16:17]
	v_mov_b64_e32 v[30:31], v[18:19]
	s_barrier
	s_cbranch_vccnz .LBB0_224
	s_branch .LBB0_269

; __device__ void phase_attn(const P& p) {
;   int wid = __builtin_amdgcn_readfirstlane(opaque_tid(p) >> 6);
;   for (int u = blockIdx.x * 8 + wid; u < 32768 / ATT_NT; u += gridDim.x * 8) attn_unitN<ATT_NT>(p, u);
; }
.Lmy_attn_done:
	s_cmpk_lt_u32 s33, 0x100
	s_cbranch_scc1 .LBB0_330
	s_branch .Lmy_scan

; __device__ void phase_gla_scan(const P& p) {
;   u16* kv = (u16*)((char*)p.out + OUT_KV);
;   const float* dec = (const float*)(p.ws + OFF_DEC);
;   int tid = opaque_tid(p);
;   for (int it = blockIdx.x; it < 768; it += gridDim.x) {
;     int chunk0, nc, q;
;     if (it < 256) { q = it; int seq = q >> 6; chunk0 = 512 + seq * 128; nc = 128; q &= 63; }
;     else { q = it - 256; int seq = q >> 6; chunk0 = seq * 64; nc = 64; q &= 63; }
;     int h = q >> 4, dir = (q >> 3) & 1, sl = q & 7;
;     int e0 = sl * 1024 + tid * 2;
;     int dk = e0 & 63;
;     float s0 = 0.f, s1 = 0.f;
.LBB0_321:
	s_or_b64 exec, exec, s[0:1]
	s_cmpk_gt_i32 s2, 0x2ff
	s_waitcnt lgkmcnt(0)
	s_barrier
	s_cmpk_lt_u32 s33, 0x100
	s_cbranch_scc0 .LBB0_229
.Lmy_scan:
	s_cmpk_gt_i32 s2, 0x2ff
	v_mbcnt_lo_u32_b32 v0, -1, 0
	v_mbcnt_hi_u32_b32 v0, -1, v0
	s_cbranch_scc1 .Lmy_scan_done
	v_readlane_b32 s0, v255, 0
	s_lshl_b32 s0, s0, 1
	s_and_b32 s0, s0, 0xffffff80
	v_lshl_add_u32 v8, v0, 1, s0
	v_lshlrev_b32_e32 v0, 3, v0
	v_and_b32_e32 v0, 0xf8, v0
	v_mov_b32_e32 v1, 0
	v_lshl_add_u64 v[0:1], s[34:35], 0, v[0:1]
	s_mov_b64 s[0:1], 0x1f400000
	v_lshl_add_u64 v[0:1], v[0:1], 0, s[0:1]
	s_mov_b32 s3, s2

; __device__ __forceinline__ float bf2f(u16 h) { return __uint_as_float(((unsigned)h) << 16); }
; __device__ void phase_gla_scan(const P& p) {
;     ...
;   for (int it = blockIdx.x; it < 768; it += gridDim.x) {
;     int chunk0, nc, q;
;     if (it < 256) { q = it; int seq = q >> 6; chunk0 = 512 + seq * 128; nc = 128; q &= 63; }
;     else { q = it - 256; int seq = q >> 6; chunk0 = seq * 64; nc = 64; q &= 63; }
;     int h = q >> 4, dir = (q >> 3) & 1, sl = q & 7;
;     int e0 = sl * 1024 + tid * 2;
;     int dk = e0 & 63;
;     float s0 = 0.f, s1 = 0.f;
;     for (int n8 = 0; n8 < nc; n8 += 8) {
;       unsigned kvv[8]; float2 dd[8];
; #pragma unroll
;       for (int i = 0; i < 8; ++i) {
;         int n = n8 + i;
;         int chunk = dir == 0 ? chunk0 + n : chunk0 + nc - 1 - n;
;         size_t base = (size_t)((chunk * 4 + h) * 2 + dir);
;         kvv[i] = *(const unsigned*)(kv + base * 8192 + e0);
;         dd[i] = *(const float2*)(dec + base * 64 + dk);
;       }
; #pragma unroll
;       for (int i = 0; i < 8; ++i) {
;         int n = n8 + i;
;         int chunk = dir == 0 ? chunk0 + n : chunk0 + nc - 1 - n;
;         size_t base = (size_t)((chunk * 4 + h) * 2 + dir);
;         *(unsigned*)(kv + base * 8192 + e0) = pack2(s0, s1);
;         s0 = dd[i].x * s0 + bf2f((u16)(kvv[i] & 0xffff));
;         s1 = dd[i].y * s1 + bf2f((u16)(kvv[i] >> 16));
;       }
;     }
;   }
.Lmy_scan_done:
	s_cmpk_lt_u32 s33, 0x100
	s_cbranch_scc1 .LBB0_229
